# attention loops: merged lgkmcnt waits (D 14->6, MLA 29->11 per iteration)
# speedup vs baseline: 1.0028x; 1.0028x over previous
; #define ALAS __attribute__((address_space(3)))
; #define AMFMA(a, b, c) __builtin_amdgcn_mfma_f32_32x32x16_bf16((a), (b), (c), 0, 0, 0)
; template <bool SUB> __device__ __forceinline__ void attn_unit_r2(const AU& u, ALAS unsigned char* lds, float mb2) {
;     ...
;             f32x16 Sa0 = negm, Sa1 = negm, Sb0 = negm, Sb1 = negm;
; #pragma unroll
;             for (int d0 = 0; d0 < 4; ++d0) {
;                 const bf16x8 k0 = *(const ALAS bf16x8*)(kb + d0 * 32), k1 = *(const ALAS bf16x8*)(kb + 32 * KP + d0 * 32);
;                 Sa0 = AMFMA(k0, qa[d0], Sa0); Sa1 = AMFMA(k1, qa[d0], Sa1); Sb0 = AMFMA(k0, qb[d0], Sb0); Sb1 = AMFMA(k1, qb[d0], Sb1);
;             }
.Lr2n_noload:
	ds_read_b128 v[222:225], v168 offset:0
	ds_read_b128 v[226:229], v168 offset:32
	ds_read_b128 v[230:233], v168 offset:64
	ds_read_b128 v[234:237], v168 offset:96
	v_mfma_f32_32x32x16_bf16 v[48:63], v[178:181], v[238:241], v[48:63]
	v_add_f32_e32 v172, v96, v172
	v_add_f32_e32 v173, v80, v173
	v_add_f32_e32 v172, v97, v172
	v_add_f32_e32 v173, v81, v173
	v_mfma_f32_32x32x16_bf16 v[64:79], v[178:181], v[248:251], v[64:79]
	v_add_f32_e32 v172, v98, v172
	v_add_f32_e32 v173, v82, v173
	v_add_f32_e32 v172, v99, v172
	v_add_f32_e32 v173, v83, v173
	ds_read_b128 v[178:181], v168 offset:4608
	v_mfma_f32_32x32x16_bf16 v[16:31], v[182:185], v[238:241], v[16:31]
	v_add_f32_e32 v172, v100, v172
	v_add_f32_e32 v173, v84, v173
	v_add_f32_e32 v172, v101, v172
	v_add_f32_e32 v173, v85, v173
	v_mfma_f32_32x32x16_bf16 v[32:47], v[182:185], v[248:251], v[32:47]
	v_add_f32_e32 v172, v102, v172
	v_add_f32_e32 v173, v86, v173
	v_add_f32_e32 v172, v103, v172
	v_add_f32_e32 v173, v87, v173
	ds_read_b128 v[182:185], v168 offset:4640
	v_mfma_f32_32x32x16_bf16 v[48:63], v[186:189], v[194:197], v[48:63]
	v_add_f32_e32 v172, v104, v172
	v_add_f32_e32 v173, v88, v173
	v_add_f32_e32 v172, v105, v172
	v_add_f32_e32 v173, v89, v173
	v_mfma_f32_32x32x16_bf16 v[64:79], v[186:189], v[210:213], v[64:79]
	v_add_f32_e32 v172, v106, v172
	v_add_f32_e32 v173, v90, v173
	v_add_f32_e32 v172, v107, v172
	v_add_f32_e32 v173, v91, v173
	ds_read_b128 v[186:189], v168 offset:4672
	v_mfma_f32_32x32x16_bf16 v[16:31], v[190:193], v[194:197], v[16:31]
	v_add_f32_e32 v172, v108, v172
	v_add_f32_e32 v173, v92, v173
	v_add_f32_e32 v172, v109, v172
	v_add_f32_e32 v173, v93, v173
	v_mfma_f32_32x32x16_bf16 v[32:47], v[190:193], v[210:213], v[32:47]
	v_add_f32_e32 v172, v110, v172
	v_add_f32_e32 v173, v94, v173
	v_add_f32_e32 v172, v111, v172
	v_add_f32_e32 v173, v95, v173
	ds_read_b128 v[190:193], v168 offset:4704
	s_waitcnt lgkmcnt(4)
	v_mfma_f32_32x32x16_bf16 v[96:111], v[222:225], v[136:139], 0
	v_lshl_add_u64 v[174:175], v[174:175], 0, s[12:13]
	v_add_f32_e32 v242, v112, v242
	v_add_f32_e32 v243, v0, v243
	v_add_f32_e32 v242, v113, v242
	v_add_f32_e32 v243, v1, v243
	v_add_f32_e32 v242, v114, v242
	v_mfma_f32_32x32x16_bf16 v[96:111], v[226:229], v[140:143], v[96:111]
	v_lshl_add_u64 v[176:177], v[176:177], 0, s[12:13]
	v_add_f32_e32 v243, v2, v243
	v_add_f32_e32 v242, v115, v242
	v_add_f32_e32 v243, v3, v243
	v_add_f32_e32 v242, v116, v242
	v_add_f32_e32 v243, v4, v243
	v_mfma_f32_32x32x16_bf16 v[96:111], v[230:233], v[144:147], v[96:111]
	v_add_f32_e32 v242, v117, v242
	v_add_f32_e32 v243, v5, v243
	v_add_f32_e32 v242, v118, v242
	v_add_f32_e32 v243, v6, v243
	v_add_f32_e32 v242, v119, v242
	v_add_f32_e32 v243, v7, v243
	v_mfma_f32_32x32x16_bf16 v[96:111], v[234:237], v[148:151], v[96:111]
	v_add_f32_e32 v242, v120, v242
	v_add_f32_e32 v243, v8, v243
	v_add_f32_e32 v242, v121, v242
	v_add_f32_e32 v243, v9, v243
	v_add_f32_e32 v242, v122, v242
	v_add_f32_e32 v243, v10, v243
	v_add_f32_e32 v242, v123, v242
	v_add_f32_e32 v243, v11, v243
	v_mfma_f32_32x32x16_bf16 v[80:95], v[222:225], v[152:155], 0
	v_add_f32_e32 v242, v124, v242
	v_add_f32_e32 v243, v12, v243
	v_add_f32_e32 v242, v125, v242
	v_add_f32_e32 v243, v13, v243
	v_add_f32_e32 v242, v126, v242
	v_add_f32_e32 v243, v14, v243
	v_add_f32_e32 v242, v127, v242
	v_add_f32_e32 v243, v15, v243
	v_mfma_f32_32x32x16_bf16 v[80:95], v[226:229], v[156:159], v[80:95]
	v_exp_f32_e32 v96, v96
	v_exp_f32_e32 v97, v97
	v_exp_f32_e32 v98, v98
	v_exp_f32_e32 v99, v99
	v_mfma_f32_32x32x16_bf16 v[80:95], v[230:233], v[160:163], v[80:95]
	v_exp_f32_e32 v100, v100
	v_exp_f32_e32 v101, v101
	v_exp_f32_e32 v102, v102
	v_exp_f32_e32 v103, v103
	v_mfma_f32_32x32x16_bf16 v[80:95], v[234:237], v[164:167], v[80:95]
	v_exp_f32_e32 v104, v104
	v_exp_f32_e32 v105, v105
	v_exp_f32_e32 v106, v106
	v_exp_f32_e32 v107, v107
	s_waitcnt lgkmcnt(0)
; #define ALAS __attribute__((address_space(3)))
; __device__ __forceinline__ s16x4 vtr(const ALAS unsigned char* p) { return __builtin_bit_cast(s16x4, __builtin_amdgcn_ds_read_tr16_b64_v4i16((ALAS s16x4*)p)); }
; #define AMFMA(a, b, c) __builtin_amdgcn_mfma_f32_32x32x16_bf16((a), (b), (c), 0, 0, 0)
; template <bool SUB> __device__ __forceinline__ void attn_unit_r2(const AU& u, ALAS unsigned char* lds, float mb2) {
;     ...
;                 const bf16x8 k0 = *(const ALAS bf16x8*)(kb + d0 * 32), k1 = *(const ALAS bf16x8*)(kb + 32 * KP + d0 * 32);
;                 Sa0 = AMFMA(k0, qa[d0], Sa0); Sa1 = AMFMA(k1, qa[d0], Sa1); Sb0 = AMFMA(k0, qb[d0], Sb0); Sb1 = AMFMA(k1, qb[d0], Sb1);
;             }
;             bf16x8 paa[4], pab[4];
;     ...
;             R2_SOFT(Sa0, Sa1, paa, la);
;             R2_SOFT(Sb0, Sb1, pab, lb);
;     ...
; #pragma unroll
;             for (int ks = 0; ks < 4; ++ks) {
;                 const s16x4 lo0 = vtr(vb + ks * 16 * VP), hi0 = vtr(vb + (ks * 16 + 8) * VP), lo1 = vtr(vb + ks * 16 * VP + 64), hi1 = vtr(vb + (ks * 16 + 8) * VP + 64);
;                 const bf16x8 vf0 = __builtin_shufflevector(lo0, hi0, 0, 1, 2, 3, 4, 5, 6, 7), vf1 = __builtin_shufflevector(lo1, hi1, 0, 1, 2, 3, 4, 5, 6, 7);
;                 oa0 = AMFMA(paa[ks], vf0, oa0); oa1 = AMFMA(paa[ks], vf1, oa1); ob0 = AMFMA(pab[ks], vf0, ob0); ob1 = AMFMA(pab[ks], vf1, ob1);
;             }
	v_mfma_f32_32x32x16_bf16 v[112:127], v[178:181], v[136:139], 0
	v_exp_f32_e32 v108, v108
	v_exp_f32_e32 v109, v109
	v_exp_f32_e32 v110, v110
	v_exp_f32_e32 v111, v111
	v_mfma_f32_32x32x16_bf16 v[112:127], v[182:185], v[140:143], v[112:127]
	v_cvt_pk_bf16_f32 v222, v96, v97
	v_cvt_pk_bf16_f32 v223, v98, v99
	v_cvt_pk_bf16_f32 v224, v100, v101
	v_cvt_pk_bf16_f32 v225, v102, v103
	v_exp_f32_e32 v80, v80
	v_exp_f32_e32 v81, v81
	v_mfma_f32_32x32x16_bf16 v[112:127], v[186:189], v[144:147], v[112:127]
	v_exp_f32_e32 v82, v82
	v_exp_f32_e32 v83, v83
	v_exp_f32_e32 v84, v84
	v_exp_f32_e32 v85, v85
	v_mfma_f32_32x32x16_bf16 v[112:127], v[190:193], v[148:151], v[112:127]
	v_exp_f32_e32 v86, v86
	v_exp_f32_e32 v87, v87
	v_cvt_pk_bf16_f32 v230, v104, v105
	v_cvt_pk_bf16_f32 v231, v106, v107
	v_cvt_pk_bf16_f32 v232, v108, v109
	v_cvt_pk_bf16_f32 v233, v110, v111
	v_mfma_f32_32x32x16_bf16 v[0:15], v[178:181], v[152:155], 0
	v_exp_f32_e32 v88, v88
	v_exp_f32_e32 v89, v89
	v_exp_f32_e32 v90, v90
	v_exp_f32_e32 v91, v91
	ds_read_b64_tr_b16 v[238:239], v221 offset:18432
	ds_read_b64_tr_b16 v[240:241], v221 offset:19584
	ds_read_b64_tr_b16 v[248:249], v221 offset:18496
	ds_read_b64_tr_b16 v[250:251], v221 offset:19648
	v_mfma_f32_32x32x16_bf16 v[0:15], v[182:185], v[156:159], v[0:15]
	v_exp_f32_e32 v92, v92
	v_exp_f32_e32 v93, v93
	v_exp_f32_e32 v94, v94
	v_exp_f32_e32 v95, v95
	v_mfma_f32_32x32x16_bf16 v[0:15], v[186:189], v[160:163], v[0:15]
	v_cvt_pk_bf16_f32 v226, v80, v81
	v_cvt_pk_bf16_f32 v227, v82, v83
	v_cvt_pk_bf16_f32 v228, v84, v85
	v_cvt_pk_bf16_f32 v229, v86, v87
	v_exp_f32_e32 v112, v112
	v_exp_f32_e32 v113, v113
	v_mfma_f32_32x32x16_bf16 v[0:15], v[190:193], v[164:167], v[0:15]
	v_exp_f32_e32 v114, v114
	v_exp_f32_e32 v115, v115
	v_exp_f32_e32 v116, v116
	v_exp_f32_e32 v117, v117
	ds_read_b64_tr_b16 v[194:195], v221 offset:20736
	ds_read_b64_tr_b16 v[196:197], v221 offset:21888
	ds_read_b64_tr_b16 v[210:211], v221 offset:20800
	ds_read_b64_tr_b16 v[212:213], v221 offset:21952
	s_waitcnt lgkmcnt(4)
	v_mfma_f32_32x32x16_bf16 v[48:63], v[222:225], v[238:241], v[48:63]
	v_exp_f32_e32 v118, v118
	v_exp_f32_e32 v119, v119
	v_exp_f32_e32 v120, v120
	v_exp_f32_e32 v121, v121
	v_mfma_f32_32x32x16_bf16 v[64:79], v[222:225], v[248:251], v[64:79]
	v_cvt_pk_bf16_f32 v234, v88, v89
	v_cvt_pk_bf16_f32 v235, v90, v91
	v_cvt_pk_bf16_f32 v236, v92, v93
	v_cvt_pk_bf16_f32 v237, v94, v95
	v_exp_f32_e32 v122, v122
	v_exp_f32_e32 v123, v123
	v_mfma_f32_32x32x16_bf16 v[16:31], v[226:229], v[238:241], v[16:31]
	v_exp_f32_e32 v124, v124
	v_exp_f32_e32 v125, v125
	v_exp_f32_e32 v126, v126
	v_exp_f32_e32 v127, v127
	v_mfma_f32_32x32x16_bf16 v[32:47], v[226:229], v[248:251], v[32:47]
	ds_read_b64_tr_b16 v[238:239], v221 offset:23040
	ds_read_b64_tr_b16 v[240:241], v221 offset:24192
	ds_read_b64_tr_b16 v[248:249], v221 offset:23104
	ds_read_b64_tr_b16 v[250:251], v221 offset:24256
	v_exp_f32_e32 v0, v0
	v_exp_f32_e32 v1, v1
	v_exp_f32_e32 v2, v2
	v_exp_f32_e32 v3, v3
	s_waitcnt lgkmcnt(4)
	v_mfma_f32_32x32x16_bf16 v[48:63], v[230:233], v[194:197], v[48:63]
	v_exp_f32_e32 v4, v4
	v_exp_f32_e32 v5, v5
	v_exp_f32_e32 v6, v6
	v_exp_f32_e32 v7, v7
	v_mfma_f32_32x32x16_bf16 v[64:79], v[230:233], v[210:213], v[64:79]
	v_cvt_pk_bf16_f32 v178, v112, v113
	v_cvt_pk_bf16_f32 v179, v114, v115
	v_cvt_pk_bf16_f32 v180, v116, v117
	v_cvt_pk_bf16_f32 v181, v118, v119
	v_exp_f32_e32 v8, v8
	v_exp_f32_e32 v9, v9
	v_mfma_f32_32x32x16_bf16 v[16:31], v[234:237], v[194:197], v[16:31]
	v_exp_f32_e32 v10, v10
	v_exp_f32_e32 v11, v11
	v_exp_f32_e32 v12, v12
	v_exp_f32_e32 v13, v13
	s_andn2_b64 vcc, exec, s[54:55]
	v_mfma_f32_32x32x16_bf16 v[32:47], v[234:237], v[210:213], v[32:47]
	ds_read_b64_tr_b16 v[194:195], v221 offset:25344
	ds_read_b64_tr_b16 v[196:197], v221 offset:26496
	ds_read_b64_tr_b16 v[210:211], v221 offset:25408
	ds_read_b64_tr_b16 v[212:213], v221 offset:26560
	v_exp_f32_e32 v14, v14
	v_exp_f32_e32 v15, v15
	v_cvt_pk_bf16_f32 v182, v0, v1
	v_cvt_pk_bf16_f32 v183, v2, v3
	v_cvt_pk_bf16_f32 v184, v4, v5
	v_cvt_pk_bf16_f32 v185, v6, v7
	v_cvt_pk_bf16_f32 v186, v120, v121
	v_cvt_pk_bf16_f32 v187, v122, v123
	v_cvt_pk_bf16_f32 v188, v124, v125
	v_cvt_pk_bf16_f32 v189, v126, v127
	v_cvt_pk_bf16_f32 v190, v8, v9
	v_cvt_pk_bf16_f32 v191, v10, v11
	v_cvt_pk_bf16_f32 v192, v12, v13
	v_cvt_pk_bf16_f32 v193, v14, v15
	s_cbranch_vccnz .Lr2n_nowrite
	s_waitcnt vmcnt(0)
	ds_write_b128 v220, v[128:131]
	ds_write_b128 v220, v[132:135] offset:18432

; #define ALAS __attribute__((address_space(3)))
; #define AMFMA(a, b, c) __builtin_amdgcn_mfma_f32_32x32x16_bf16((a), (b), (c), 0, 0, 0)
; template <bool SUB> __device__ __forceinline__ void attn_unit_r2b(const AU& u, ALAS unsigned char* lds, float mb2) {
;     ...
;             const ALAS unsigned char* kb = lds + cur * KBUF + r * KP + h * 16;
;             const ALAS unsigned char* vb = lds + V_OFF + cur * VBUF + (4 * h + ((lane & 15) >> 2)) * VP + ((lane >> 4) & 1) * 32 + (lane & 3) * 8;
;             bf16x8 paa[4], pab[4];
;             f32x16 Sa0, Sa1, Sb0, Sb1;
; #pragma unroll
;             for (int i = 0; i < 16; ++i) { Sa0[i] = 0.f; Sa1[i] = 0.f; Sb0[i] = 0.f; Sb1[i] = 0.f; }
; #pragma unroll
;             for (int d0 = 0; d0 < 6; ++d0) {
;                 const bf16x8 k0 = *(const ALAS bf16x8*)(kb + d0 * 32), k1 = *(const ALAS bf16x8*)(kb + 32 * KP + d0 * 32); const bf16x8 qbv = *(const ALAS bf16x8*)(qbl + d0 * 1024);
;                 Sa0 = AMFMA(k0, qa[d0], Sa0); Sa1 = AMFMA(k1, qa[d0], Sa1); Sb0 = AMFMA(k0, qbv, Sb0); Sb1 = AMFMA(k1, qbv, Sb1);
;                 if (d0 & 1) __builtin_amdgcn_sched_barrier(0);
;             }
;     ...
;             R2B_SOFT(Sa0, Sa1, paa, la);
.Lr2b_noload:
	s_and_b32 s58, s62, 1
	s_mul_i32 s34, s58, 0x3400
	v_add_u32_e32 v188, s34, v168
	ds_read_b128 v[218:221], v188 offset:0
	ds_read_b128 v[222:225], v188 offset:32
	ds_read_b128 v[226:229], v188 offset:64
	ds_read_b128 v[230:233], v188 offset:96
	ds_read_b128 v[234:237], v188 offset:128
	ds_read_b128 v[238:241], v188 offset:160
	ds_read_b128 v[176:179], v193 offset:45056
	ds_read_b128 v[180:183], v193 offset:46080
	ds_read_b128 v[184:187], v193 offset:47104
	ds_read_b128 v[248:251], v193 offset:48128
	ds_read_b128 v[244:247], v193 offset:49152
	s_mul_i32 s34, s58, 0x2400
	v_add_u32_e32 v189, s34, v197
	s_waitcnt lgkmcnt(5)
	v_mfma_f32_32x32x16_bf16 v[96:111], v[218:221], v[128:131], 0
	v_lshl_add_u64 v[166:167], v[166:167], 0, s[8:9]
	v_add_f32_e32 v242, v112, v242
	v_add_f32_e32 v243, v80, v243
	v_add_f32_e32 v242, v113, v242
	v_add_f32_e32 v243, v81, v243
	v_mfma_f32_32x32x16_bf16 v[96:111], v[222:225], v[132:135], v[96:111]
	v_lshl_add_u64 v[172:173], v[172:173], 0, s[12:13]
	v_add_f32_e32 v242, v114, v242
	v_add_f32_e32 v243, v82, v243
	v_add_f32_e32 v242, v115, v242
	v_add_f32_e32 v243, v83, v243
	v_mfma_f32_32x32x16_bf16 v[96:111], v[226:229], v[136:139], v[96:111]
	v_lshl_add_u64 v[174:175], v[174:175], 0, s[12:13]
	v_add_f32_e32 v242, v116, v242
	v_add_f32_e32 v243, v84, v243
	v_add_f32_e32 v242, v117, v242
	v_add_f32_e32 v243, v85, v243
	v_mfma_f32_32x32x16_bf16 v[96:111], v[230:233], v[140:143], v[96:111]
	v_add_f32_e32 v242, v118, v242
	v_add_f32_e32 v243, v86, v243
	v_add_f32_e32 v242, v119, v242
	v_add_f32_e32 v243, v87, v243
	v_add_f32_e32 v242, v120, v242
	v_mfma_f32_32x32x16_bf16 v[96:111], v[234:237], v[144:147], v[96:111]
	v_add_f32_e32 v243, v88, v243
	v_add_f32_e32 v242, v121, v242
	v_add_f32_e32 v243, v89, v243
	v_add_f32_e32 v242, v122, v242
	v_add_f32_e32 v243, v90, v243
	v_add_f32_e32 v242, v123, v242
	v_mfma_f32_32x32x16_bf16 v[96:111], v[238:241], v[148:151], v[96:111]
	v_add_f32_e32 v243, v91, v243
	v_add_f32_e32 v242, v124, v242
	v_add_f32_e32 v243, v92, v243
	v_add_f32_e32 v242, v125, v242
	v_add_f32_e32 v243, v93, v243
	v_add_f32_e32 v242, v126, v242
	s_waitcnt lgkmcnt(0)
	v_mfma_f32_32x32x16_bf16 v[64:79], v[218:221], v[176:179], 0
	ds_read_b128 v[176:179], v193 offset:50176
	ds_read_b128 v[218:221], v188 offset:6656
	v_add_f32_e32 v243, v94, v243
	v_add_f32_e32 v242, v127, v242
	v_add_f32_e32 v243, v95, v243
	v_mfma_f32_32x32x16_bf16 v[64:79], v[222:225], v[180:183], v[64:79]
	ds_read_b128 v[222:225], v188 offset:6688
	v_exp_f32_e32 v96, v96
	v_exp_f32_e32 v97, v97
	v_mfma_f32_32x32x16_bf16 v[64:79], v[226:229], v[184:187], v[64:79]
	ds_read_b128 v[226:229], v188 offset:6720
	v_exp_f32_e32 v98, v98
	v_exp_f32_e32 v99, v99
	v_mfma_f32_32x32x16_bf16 v[64:79], v[230:233], v[248:251], v[64:79]
	ds_read_b128 v[230:233], v188 offset:6752
	v_exp_f32_e32 v100, v100
	v_exp_f32_e32 v101, v101
	v_mfma_f32_32x32x16_bf16 v[64:79], v[234:237], v[244:247], v[64:79]
	ds_read_b128 v[234:237], v188 offset:6784
	v_exp_f32_e32 v102, v102
	v_exp_f32_e32 v103, v103
	s_waitcnt lgkmcnt(5)
	v_mfma_f32_32x32x16_bf16 v[64:79], v[238:241], v[176:179], v[64:79]
	ds_read_b128 v[238:241], v188 offset:6816
	ds_read_b128 v[176:179], v193 offset:45056
	v_exp_f32_e32 v104, v104
	v_exp_f32_e32 v105, v105
	v_exp_f32_e32 v106, v106
	v_exp_f32_e32 v107, v107
	s_waitcnt lgkmcnt(1)
	v_mfma_f32_32x32x16_bf16 v[112:127], v[218:221], v[128:131], 0
	v_exp_f32_e32 v108, v108
	v_exp_f32_e32 v109, v109
	v_exp_f32_e32 v110, v110
	v_exp_f32_e32 v111, v111
	v_mfma_f32_32x32x16_bf16 v[112:127], v[222:225], v[132:135], v[112:127]
	v_exp_f32_e32 v64, v64
	v_exp_f32_e32 v65, v65
	v_exp_f32_e32 v66, v66
	v_mfma_f32_32x32x16_bf16 v[112:127], v[226:229], v[136:139], v[112:127]
	v_exp_f32_e32 v67, v67
	v_exp_f32_e32 v68, v68
	v_exp_f32_e32 v69, v69
	v_mfma_f32_32x32x16_bf16 v[112:127], v[230:233], v[140:143], v[112:127]
	v_exp_f32_e32 v70, v70
	v_exp_f32_e32 v71, v71
	v_exp_f32_e32 v72, v72
	v_mfma_f32_32x32x16_bf16 v[112:127], v[234:237], v[144:147], v[112:127]
	v_exp_f32_e32 v73, v73
	v_exp_f32_e32 v74, v74
	v_exp_f32_e32 v75, v75
	v_mfma_f32_32x32x16_bf16 v[112:127], v[238:241], v[148:151], v[112:127]
	v_exp_f32_e32 v76, v76
	v_exp_f32_e32 v77, v77
	v_exp_f32_e32 v78, v78
	v_exp_f32_e32 v79, v79
	s_waitcnt lgkmcnt(0)
; #define ALAS __attribute__((address_space(3)))
; __device__ __forceinline__ s16x4 vtr(const ALAS unsigned char* p) { return __builtin_bit_cast(s16x4, __builtin_amdgcn_ds_read_tr16_b64_v4i16((ALAS s16x4*)p)); }
; #define AMFMA(a, b, c) __builtin_amdgcn_mfma_f32_32x32x16_bf16((a), (b), (c), 0, 0, 0)
; template <bool SUB> __device__ __forceinline__ void attn_unit_r2b(const AU& u, ALAS unsigned char* lds, float mb2) {
;     ...
;             R2B_SOFT(Sa0, Sa1, paa, la);
;             __builtin_amdgcn_sched_barrier(0);
;             R2B_SOFT(Sb0, Sb1, pab, lb);
;     ...
; #pragma unroll
;             for (int ks = 0; ks < 4; ++ks) {
;                 const s16x4 lo0 = vtr(vb + ks * 16 * VP), hi0 = vtr(vb + (ks * 16 + 8) * VP), lo1 = vtr(vb + ks * 16 * VP + 64), hi1 = vtr(vb + (ks * 16 + 8) * VP + 64);
;                 const bf16x8 vf0 = __builtin_shufflevector(lo0, hi0, 0, 1, 2, 3, 4, 5, 6, 7), vf1 = __builtin_shufflevector(lo1, hi1, 0, 1, 2, 3, 4, 5, 6, 7);
;                 oa0 = AMFMA(paa[ks], vf0, oa0); oa1 = AMFMA(paa[ks], vf1, oa1); ob0 = AMFMA(pab[ks], vf0, ob0); ob1 = AMFMA(pab[ks], vf1, ob1);
;             }
;         }
;         if (t + 1 < NT) { *(ALAS u32x4*)(lds + (cur ^ 1) * KBUF + kl0) = rk0; if (k2) *(ALAS u32x4*)(lds + (cur ^ 1) * KBUF + kl1) = rk1; *(ALAS u32x4*)(lds + (cur ^ 1) * VBUF + vl) = rv; }
	v_mfma_f32_32x32x16_bf16 v[80:95], v[218:221], v[176:179], 0
	ds_read_b128 v[176:179], v193 offset:50176
	v_cvt_pk_bf16_f32 v218, v96, v97
	v_cvt_pk_bf16_f32 v219, v98, v99
	v_cvt_pk_bf16_f32 v220, v100, v101
	v_cvt_pk_bf16_f32 v221, v102, v103
	v_mfma_f32_32x32x16_bf16 v[80:95], v[222:225], v[180:183], v[80:95]
	v_cvt_pk_bf16_f32 v222, v64, v65
	v_cvt_pk_bf16_f32 v223, v66, v67
	v_cvt_pk_bf16_f32 v224, v68, v69
	v_cvt_pk_bf16_f32 v225, v70, v71
	v_exp_f32_e32 v112, v112
	v_exp_f32_e32 v113, v113
	v_mfma_f32_32x32x16_bf16 v[80:95], v[226:229], v[184:187], v[80:95]
	v_cvt_pk_bf16_f32 v226, v104, v105
	v_cvt_pk_bf16_f32 v227, v106, v107
	v_cvt_pk_bf16_f32 v228, v108, v109
	v_cvt_pk_bf16_f32 v229, v110, v111
	v_exp_f32_e32 v114, v114
	v_exp_f32_e32 v115, v115
	ds_read_b64_tr_b16 v[184:185], v189 offset:26624
	ds_read_b64_tr_b16 v[186:187], v189 offset:27776
	v_mfma_f32_32x32x16_bf16 v[80:95], v[230:233], v[248:251], v[80:95]
	v_cvt_pk_bf16_f32 v230, v72, v73
	v_cvt_pk_bf16_f32 v231, v74, v75
	v_cvt_pk_bf16_f32 v232, v76, v77
	v_cvt_pk_bf16_f32 v233, v78, v79
	v_exp_f32_e32 v116, v116
	v_exp_f32_e32 v117, v117
	ds_read_b64_tr_b16 v[248:249], v189 offset:26688
	ds_read_b64_tr_b16 v[250:251], v189 offset:27840
	v_mfma_f32_32x32x16_bf16 v[80:95], v[234:237], v[244:247], v[80:95]
	v_exp_f32_e32 v118, v118
	v_exp_f32_e32 v119, v119
	v_exp_f32_e32 v120, v120
	v_exp_f32_e32 v121, v121
	ds_read_b64_tr_b16 v[244:245], v189 offset:28928
	ds_read_b64_tr_b16 v[246:247], v189 offset:30080
	s_waitcnt lgkmcnt(6)
	v_mfma_f32_32x32x16_bf16 v[80:95], v[238:241], v[176:179], v[80:95]
	v_exp_f32_e32 v122, v122
	v_exp_f32_e32 v123, v123
	v_exp_f32_e32 v124, v124
	v_exp_f32_e32 v125, v125
	s_waitcnt lgkmcnt(2)
	v_mfma_f32_32x32x16_bf16 v[32:47], v[218:221], v[184:187], v[32:47]
	v_exp_f32_e32 v126, v126
	v_exp_f32_e32 v127, v127
	v_cvt_pk_bf16_f32 v234, v112, v113
	v_cvt_pk_bf16_f32 v235, v114, v115
	v_cvt_pk_bf16_f32 v236, v116, v117
	v_cvt_pk_bf16_f32 v237, v118, v119
	v_mfma_f32_32x32x16_bf16 v[48:63], v[218:221], v[248:251], v[48:63]
	v_exp_f32_e32 v80, v80
	v_exp_f32_e32 v81, v81
	v_exp_f32_e32 v82, v82
	v_exp_f32_e32 v83, v83
	v_mfma_f32_32x32x16_bf16 v[0:15], v[222:225], v[184:187], v[0:15]
	ds_read_b64_tr_b16 v[184:185], v189 offset:28992
	ds_read_b64_tr_b16 v[186:187], v189 offset:30144
	v_exp_f32_e32 v84, v84
	v_exp_f32_e32 v85, v85
	v_exp_f32_e32 v86, v86
	v_exp_f32_e32 v87, v87
	v_mfma_f32_32x32x16_bf16 v[16:31], v[222:225], v[248:251], v[16:31]
	ds_read_b64_tr_b16 v[248:249], v189 offset:31232
	ds_read_b64_tr_b16 v[250:251], v189 offset:32384
	v_exp_f32_e32 v88, v88
	v_exp_f32_e32 v89, v89
	v_exp_f32_e32 v90, v90
	v_exp_f32_e32 v91, v91
	s_waitcnt lgkmcnt(2)
	v_mfma_f32_32x32x16_bf16 v[32:47], v[226:229], v[244:247], v[32:47]
	v_exp_f32_e32 v92, v92
	v_exp_f32_e32 v93, v93
	v_exp_f32_e32 v94, v94
	v_exp_f32_e32 v95, v95
	v_mfma_f32_32x32x16_bf16 v[48:63], v[226:229], v[184:187], v[48:63]
	v_cvt_pk_bf16_f32 v176, v120, v121
	v_cvt_pk_bf16_f32 v177, v122, v123
	v_cvt_pk_bf16_f32 v178, v124, v125
	v_cvt_pk_bf16_f32 v179, v126, v127
	v_cvt_pk_bf16_f32 v238, v80, v81
	v_cvt_pk_bf16_f32 v239, v82, v83
	v_cvt_pk_bf16_f32 v240, v84, v85
	v_cvt_pk_bf16_f32 v241, v86, v87
	v_mfma_f32_32x32x16_bf16 v[0:15], v[230:233], v[244:247], v[0:15]
	ds_read_b64_tr_b16 v[244:245], v189 offset:31296
	ds_read_b64_tr_b16 v[246:247], v189 offset:32448
	v_cvt_pk_bf16_f32 v180, v88, v89
	v_cvt_pk_bf16_f32 v181, v90, v91
	v_cvt_pk_bf16_f32 v182, v92, v93
	v_cvt_pk_bf16_f32 v183, v94, v95
	v_add_f32_e32 v164, v96, v164
	v_add_f32_e32 v165, v64, v165
	v_add_f32_e32 v164, v97, v164
	v_mfma_f32_32x32x16_bf16 v[16:31], v[230:233], v[184:187], v[16:31]
	ds_read_b64_tr_b16 v[184:185], v189 offset:33536
	ds_read_b64_tr_b16 v[186:187], v189 offset:34688
	v_add_f32_e32 v165, v65, v165
	v_add_f32_e32 v164, v98, v164
	v_add_f32_e32 v165, v66, v165
	v_add_f32_e32 v164, v99, v164
	v_add_f32_e32 v165, v67, v165
	s_waitcnt lgkmcnt(2)
	v_mfma_f32_32x32x16_bf16 v[32:47], v[234:237], v[248:251], v[32:47]
	v_add_f32_e32 v164, v100, v164
	v_add_f32_e32 v165, v68, v165
	v_add_f32_e32 v164, v101, v164
	v_add_f32_e32 v165, v69, v165
	v_add_f32_e32 v164, v102, v164
	v_add_f32_e32 v165, v70, v165
	v_mfma_f32_32x32x16_bf16 v[48:63], v[234:237], v[244:247], v[48:63]
	v_add_f32_e32 v164, v103, v164
	v_add_f32_e32 v165, v71, v165
	v_add_f32_e32 v164, v104, v164
	v_add_f32_e32 v165, v72, v165
	v_add_f32_e32 v164, v105, v164
	v_add_f32_e32 v165, v73, v165
	v_mfma_f32_32x32x16_bf16 v[0:15], v[238:241], v[248:251], v[0:15]
	ds_read_b64_tr_b16 v[248:249], v189 offset:33600
	ds_read_b64_tr_b16 v[250:251], v189 offset:34752
	v_add_f32_e32 v164, v106, v164
	v_add_f32_e32 v165, v74, v165
	v_add_f32_e32 v164, v107, v164
	v_add_f32_e32 v165, v75, v165
	v_add_f32_e32 v164, v108, v164
	v_mfma_f32_32x32x16_bf16 v[16:31], v[238:241], v[244:247], v[16:31]
	v_add_f32_e32 v165, v76, v165
	v_add_f32_e32 v164, v109, v164
	v_add_f32_e32 v165, v77, v165
	v_add_f32_e32 v164, v110, v164
	v_add_f32_e32 v165, v78, v165
	v_add_f32_e32 v164, v111, v164
	s_waitcnt lgkmcnt(0)
	v_mfma_f32_32x32x16_bf16 v[32:47], v[176:179], v[184:187], v[32:47]
	v_add_f32_e32 v165, v79, v165
	s_andn2_b64 vcc, exec, s[56:57]
	v_mfma_f32_32x32x16_bf16 v[48:63], v[176:179], v[248:251], v[48:63]
	s_cbranch_vccnz .Lr2b_nowrite
	s_xor_b32 s58, s58, 1
	s_mul_i32 s34, s58, 0x3400
	v_add_u32_e32 v217, s34, v194
	s_waitcnt vmcnt(0)
	ds_write_b128 v217, v[152:155]
	s_and_saveexec_b64 s[56:57], s[40:41]
	s_cbranch_execz .Lr2b_nok2w
	v_add_u32_e32 v217, s34, v195
	ds_write_b128 v217, v[156:159]
